# same dense-loop edits plus 48 bytes of padding after the dense loop: bf16 GEMM loop head lands 64-byte aligned
# speedup vs baseline: 1.0018x; 1.0018x over previous
; #define AF_WAIT_BAR(N) asm volatile("s_waitcnt vmcnt(" #N ") lgkmcnt(0)\n\ts_barrier" ::: "memory")
; #define AF_ROT() do { s_prev = s_cur; s_cur = s_next; s_next = (s_next == 2) ? 0 : s_next + 1; } while (0)
; #define AF_WAIT_BAR(N) asm volatile("s_waitcnt vmcnt(" #N ") lgkmcnt(0)\n\ts_barrier" ::: "memory")
; #define AF_ROT() do { s_prev = s_cur; s_cur = s_next; s_next = (s_next == 2) ? 0 : s_next + 1; } while (0)
; __device__ __forceinline__ void dense_unit(int b, int h, int qb, const bf16* Q, const bf16* __restrict__ KV, const char* __restrict__ K6N, const char* __restrict__ K6R, bf16* O, char* shm, const int tid) {
;     ...
;   int t = 1;
;   for (; t + 3 < NT; t += 2) {
;     AF_STEP(pB0, pB1, pA0, pA1, t, true, true, true);     AF_WAIT_BAR(2); AF_ROT();
.LBB0_65:
	v_lshl_add_u32 v145, s52, 13, v157
	ds_read_b64_tr_b16 v[98:99], v145 offset:15360
	ds_read_b64_tr_b16 v[100:101], v145 offset:15872
	v_add_f32_e32 v208, v50, v51
	ds_read_b64_tr_b16 v[102:103], v145 offset:19456
	ds_read_b64_tr_b16 v[104:105], v145 offset:19968
	v_add_f32_e32 v209, v52, v53
	v_add_f32_e32 v208, v54, v208
	v_add_f32_e32 v209, v55, v209
	v_add_f32_e32 v208, v56, v208
	v_add_f32_e32 v209, v57, v209
	v_add_f32_e32 v208, v58, v208
	v_cvt_pk_bf16_f32 v106, v50, v51
	v_cvt_pk_bf16_f32 v107, v52, v53
	v_cvt_pk_bf16_f32 v108, v54, v55
	v_cvt_pk_bf16_f32 v109, v56, v57
	v_mfma_scale_f32_32x32x64_f8f6f4 v[82:97], v[72:77], v[120:125], 0, v139, v0 op_sel_hi:[0,0,0] cbsz:2 blgp:2
	ds_read_b64_tr_b16 v[54:55], v145 offset:16384
	ds_read_b64_tr_b16 v[56:57], v145 offset:16896
	ds_read_b64_tr_b16 v[110:111], v145 offset:20480
	ds_read_b64_tr_b16 v[112:113], v145 offset:20992
	v_add_f32_e32 v209, v59, v209
	v_mfma_scale_f32_32x32x64_f8f6f4 v[66:81], v[66:71], v[120:125], 0, v139, v0 op_sel_hi:[0,0,0] cbsz:2 blgp:2
	v_add_f32_e32 v208, v60, v208
	v_add_f32_e32 v209, v61, v209
	v_add_f32_e32 v208, v62, v208
	v_add_f32_e32 v209, v63, v209
	v_add_f32_e32 v208, v64, v208
	v_add_f32_e32 v209, v65, v209
	v_add_f32_e32 v208, v34, v208
	v_cvt_pk_bf16_f32 v58, v58, v59
	v_cvt_pk_bf16_f32 v59, v60, v61
	v_cvt_pk_bf16_f32 v60, v62, v63
	v_cvt_pk_bf16_f32 v61, v64, v65
	ds_read_b64_tr_b16 v[62:63], v145 offset:17408
	ds_read_b64_tr_b16 v[64:65], v145 offset:17920
	ds_read_b64_tr_b16 v[50:51], v145 offset:21504
	ds_read_b64_tr_b16 v[52:53], v145 offset:22016
	v_mfma_scale_f32_32x32x64_f8f6f4 v[82:97], v[132:137], v[114:119], v[82:97], v139, v0 op_sel_hi:[0,0,0] cbsz:2 blgp:2
	v_add_f32_e32 v209, v35, v209
	v_add_f32_e32 v208, v36, v208
	v_add_f32_e32 v209, v37, v209
	v_add_f32_e32 v208, v38, v208
	v_add_f32_e32 v209, v39, v209
	v_add_f32_e32 v208, v40, v208
	v_add_f32_e32 v209, v41, v209
	v_add_f32_e32 v208, v42, v208
	v_cvt_pk_bf16_f32 v132, v34, v35
	v_cvt_pk_bf16_f32 v133, v36, v37
	v_cvt_pk_bf16_f32 v134, v38, v39
	v_cvt_pk_bf16_f32 v135, v40, v41
	s_mul_i32 s13, s62, 0x1400
	s_add_i32 m0, s13, s59
	ds_read_b64_tr_b16 v[164:165], v145 offset:18432
	ds_read_b64_tr_b16 v[166:167], v145 offset:18944
	global_load_lds_dwordx4 v151, s[22:23]
	ds_read_b64_tr_b16 v[174:175], v145 offset:22528
	ds_read_b64_tr_b16 v[176:177], v145 offset:23040
	s_add_u32 s22, s22, s56
	s_addc_u32 s23, s23, 0
	s_waitcnt lgkmcnt(14)
	v_mfma_scale_f32_32x32x64_f8f6f4 v[66:81], v[126:131], v[114:119], v[66:81], v139, v0 op_sel_hi:[0,0,0] cbsz:2 blgp:2
	v_add_f32_e32 v209, v43, v209
	v_add_f32_e32 v208, v44, v208
	v_add_f32_e32 v209, v45, v209
	v_add_f32_e32 v208, v46, v208
	v_add_f32_e32 v209, v47, v209
	v_add_f32_e32 v208, v48, v208
	v_add_f32_e32 v209, v49, v209
	v_add_f32_e32 v143, v143, v208
	v_cvt_pk_bf16_f32 v126, v42, v43
	v_cvt_pk_bf16_f32 v127, v44, v45
	v_cvt_pk_bf16_f32 v128, v46, v47
	v_cvt_pk_bf16_f32 v129, v48, v49
	s_lshl_b32 s13, s11, 13
	s_add_i32 m0, s13, s60
	v_add_f32_e32 v143, v143, v209
	global_load_lds_dwordx4 v141, s[8:9]
	s_add_u32 s8, s8, 0x40000
	s_addc_u32 s9, s9, 0
	v_mfma_f32_32x32x16_bf16 v[2:17], v[106:109], v[98:101], v[2:17]
	v_exp_f32_e32 v82, v82
	v_exp_f32_e32 v83, v83
	v_exp_f32_e32 v84, v84
	v_exp_f32_e32 v85, v85
	s_mul_i32 s52, s11, 0x1400
	v_add_u32_e32 v46, s52, v154
	v_add_u32_e32 v47, s52, v155
	ds_read_b128 v[34:37], v46
	ds_read_b64 v[38:39], v47 offset:2048
	s_waitcnt lgkmcnt(14)
	v_mfma_f32_32x32x16_bf16 v[18:33], v[106:109], v[102:105], v[18:33]
	v_exp_f32_e32 v86, v86
	v_exp_f32_e32 v87, v87
	v_exp_f32_e32 v88, v88
	v_exp_f32_e32 v89, v89
	ds_read_b128 v[40:43], v46 offset:512
	ds_read_b64 v[44:45], v47 offset:2304
	s_waitcnt lgkmcnt(14)
	v_mfma_f32_32x32x16_bf16 v[2:17], v[58:61], v[54:57], v[2:17]
	v_exp_f32_e32 v90, v90
	v_exp_f32_e32 v91, v91
	v_exp_f32_e32 v92, v92
	v_exp_f32_e32 v93, v93
	ds_read_b128 v[102:105], v46 offset:3072
	ds_read_b64 v[106:107], v47 offset:4096
	s_waitcnt lgkmcnt(14)
	v_mfma_f32_32x32x16_bf16 v[18:33], v[58:61], v[110:113], v[18:33]
	v_exp_f32_e32 v94, v94
	v_exp_f32_e32 v95, v95
	v_exp_f32_e32 v96, v96
	v_exp_f32_e32 v97, v97
	ds_read_b128 v[108:111], v46 offset:3584
	ds_read_b64 v[112:113], v47 offset:4352
	s_waitcnt lgkmcnt(14)
	v_mfma_f32_32x32x16_bf16 v[2:17], v[132:135], v[62:65], v[2:17]
	v_exp_f32_e32 v66, v66
	v_exp_f32_e32 v67, v67
	v_exp_f32_e32 v68, v68
	v_exp_f32_e32 v69, v69
	s_waitcnt lgkmcnt(12)
	v_mfma_f32_32x32x16_bf16 v[18:33], v[132:135], v[50:53], v[18:33]
	v_exp_f32_e32 v70, v70
	v_exp_f32_e32 v71, v71
	v_exp_f32_e32 v72, v72
	v_exp_f32_e32 v73, v73
	s_waitcnt lgkmcnt(10)
	v_mfma_f32_32x32x16_bf16 v[2:17], v[126:129], v[164:167], v[2:17]
	v_exp_f32_e32 v74, v74
	v_exp_f32_e32 v75, v75
	v_exp_f32_e32 v76, v76
	v_exp_f32_e32 v77, v77
	s_waitcnt lgkmcnt(8)
	v_mfma_f32_32x32x16_bf16 v[18:33], v[126:129], v[174:177], v[18:33]
	v_exp_f32_e32 v78, v78
	v_exp_f32_e32 v79, v79
	v_exp_f32_e32 v80, v80
	v_exp_f32_e32 v81, v81
	s_waitcnt vmcnt(2) lgkmcnt(0)
	s_barrier
; #define AF_WAIT_BAR(N) asm volatile("s_waitcnt vmcnt(" #N ") lgkmcnt(0)\n\ts_barrier" ::: "memory")
; #define AF_ROT() do { s_prev = s_cur; s_cur = s_next; s_next = (s_next == 2) ? 0 : s_next + 1; } while (0)
; #define AF_WAIT_BAR(N) asm volatile("s_waitcnt vmcnt(" #N ") lgkmcnt(0)\n\ts_barrier" ::: "memory")
; #define AF_ROT() do { s_prev = s_cur; s_cur = s_next; s_next = (s_next == 2) ? 0 : s_next + 1; } while (0)
; __device__ __forceinline__ void dense_unit(int b, int h, int qb, const bf16* Q, const bf16* __restrict__ KV, const char* __restrict__ K6N, const char* __restrict__ K6R, bf16* O, char* shm, const int tid) {
;     ...
;   int t = 1;
;   for (; t + 3 < NT; t += 2) {
;     AF_STEP(pB0, pB1, pA0, pA1, t, true, true, true);     AF_WAIT_BAR(2); AF_ROT();
;     AF_STEP(pA0, pA1, pB0, pB1, t + 1, true, true, true); AF_WAIT_BAR(2); AF_ROT();
;   }
	s_add_i32 s13, s11, 1
	s_cmp_lg_u32 s11, 2
	s_cselect_b32 s13, s13, 0
	v_lshl_add_u32 v145, s62, 13, v157
	ds_read_b64_tr_b16 v[126:127], v145 offset:15360
	ds_read_b64_tr_b16 v[128:129], v145 offset:15872
	v_add_f32_e32 v208, v82, v83
	ds_read_b64_tr_b16 v[130:131], v145 offset:19456
	ds_read_b64_tr_b16 v[132:133], v145 offset:19968
	v_mfma_scale_f32_32x32x64_f8f6f4 v[50:65], v[34:39], v[120:125], 0, v139, v0 op_sel_hi:[0,0,0] cbsz:2 blgp:2
	v_add_f32_e32 v209, v84, v85
	v_add_f32_e32 v208, v86, v208
	v_add_f32_e32 v209, v87, v209
	v_add_f32_e32 v208, v88, v208
	v_add_f32_e32 v209, v89, v209
	v_add_f32_e32 v208, v90, v208
	v_cvt_pk_bf16_f32 v134, v82, v83
	v_cvt_pk_bf16_f32 v135, v84, v85
	v_cvt_pk_bf16_f32 v136, v86, v87
	v_cvt_pk_bf16_f32 v137, v88, v89
	ds_read_b64_tr_b16 v[164:165], v145 offset:16384
	ds_read_b64_tr_b16 v[166:167], v145 offset:16896
	ds_read_b64_tr_b16 v[98:99], v145 offset:20480
	ds_read_b64_tr_b16 v[100:101], v145 offset:20992
	v_add_f32_e32 v209, v91, v209
	v_add_f32_e32 v208, v92, v208
	v_add_f32_e32 v209, v93, v209
	v_add_f32_e32 v208, v94, v208
	v_add_f32_e32 v209, v95, v209
	v_add_f32_e32 v208, v96, v208
	v_mfma_scale_f32_32x32x64_f8f6f4 v[34:49], v[40:45], v[120:125], 0, v139, v0 op_sel_hi:[0,0,0] cbsz:2 blgp:2
	v_add_f32_e32 v209, v97, v209
	v_add_f32_e32 v208, v66, v208
	v_cvt_pk_bf16_f32 v174, v90, v91
	v_cvt_pk_bf16_f32 v175, v92, v93
	v_cvt_pk_bf16_f32 v176, v94, v95
	v_cvt_pk_bf16_f32 v177, v96, v97
	ds_read_b64_tr_b16 v[90:91], v145 offset:17408
	ds_read_b64_tr_b16 v[92:93], v145 offset:17920
	ds_read_b64_tr_b16 v[82:83], v145 offset:21504
	ds_read_b64_tr_b16 v[84:85], v145 offset:22016
	v_mfma_scale_f32_32x32x64_f8f6f4 v[50:65], v[102:107], v[114:119], v[50:65], v139, v0 op_sel_hi:[0,0,0] cbsz:2 blgp:2
	v_add_f32_e32 v209, v67, v209
	v_add_f32_e32 v208, v68, v208
	v_add_f32_e32 v209, v69, v209
	v_add_f32_e32 v208, v70, v208
	v_add_f32_e32 v209, v71, v209
	v_add_f32_e32 v208, v72, v208
	v_add_f32_e32 v209, v73, v209
	v_add_f32_e32 v208, v74, v208
	v_cvt_pk_bf16_f32 v94, v66, v67
	v_cvt_pk_bf16_f32 v95, v68, v69
	v_cvt_pk_bf16_f32 v96, v70, v71
	v_cvt_pk_bf16_f32 v97, v72, v73
	s_add_i32 m0, s52, s59
	ds_read_b64_tr_b16 v[102:103], v145 offset:18432
	ds_read_b64_tr_b16 v[104:105], v145 offset:18944
	global_load_lds_dwordx4 v151, s[22:23]
	ds_read_b64_tr_b16 v[86:87], v145 offset:22528
	ds_read_b64_tr_b16 v[88:89], v145 offset:23040
	s_add_u32 s22, s22, s56
	s_addc_u32 s23, s23, 0
	s_waitcnt lgkmcnt(14)
	v_mfma_scale_f32_32x32x64_f8f6f4 v[34:49], v[108:113], v[114:119], v[34:49], v139, v0 op_sel_hi:[0,0,0] cbsz:2 blgp:2
	v_add_f32_e32 v209, v75, v209
	v_add_f32_e32 v208, v76, v208
	v_add_f32_e32 v209, v77, v209
	v_add_f32_e32 v208, v78, v208
	v_add_f32_e32 v209, v79, v209
	v_add_f32_e32 v208, v80, v208
	v_add_f32_e32 v209, v81, v209
	v_add_f32_e32 v143, v143, v208
	v_cvt_pk_bf16_f32 v106, v74, v75
	v_cvt_pk_bf16_f32 v107, v76, v77
	v_cvt_pk_bf16_f32 v108, v78, v79
	v_cvt_pk_bf16_f32 v109, v80, v81
	s_lshl_b32 s62, s13, 13
	s_add_i32 m0, s62, s60
	v_add_f32_e32 v143, v143, v209
	global_load_lds_dwordx4 v141, s[8:9]
	s_add_u32 s8, s8, 0x40000
	s_addc_u32 s9, s9, 0
	v_mfma_f32_32x32x16_bf16 v[2:17], v[134:137], v[126:129], v[2:17]
	v_exp_f32_e32 v50, v50
	v_exp_f32_e32 v51, v51
	v_exp_f32_e32 v52, v52
	v_exp_f32_e32 v53, v53
	s_mul_i32 s52, s13, 0x1400
	v_add_u32_e32 v78, s52, v154
	v_add_u32_e32 v79, s52, v155
	ds_read_b128 v[72:75], v78
	ds_read_b64 v[76:77], v79 offset:2048
	s_waitcnt lgkmcnt(14)
	v_mfma_f32_32x32x16_bf16 v[18:33], v[134:137], v[130:133], v[18:33]
	v_exp_f32_e32 v54, v54
	v_exp_f32_e32 v55, v55
	v_exp_f32_e32 v56, v56
	v_exp_f32_e32 v57, v57
	ds_read_b128 v[66:69], v78 offset:512
	ds_read_b64 v[70:71], v79 offset:2304
	s_waitcnt lgkmcnt(14)
	v_mfma_f32_32x32x16_bf16 v[2:17], v[174:177], v[164:167], v[2:17]
	v_exp_f32_e32 v58, v58
	v_exp_f32_e32 v59, v59
	v_exp_f32_e32 v60, v60
	v_exp_f32_e32 v61, v61
	ds_read_b128 v[132:135], v78 offset:3072
	ds_read_b64 v[136:137], v79 offset:4096
	s_waitcnt lgkmcnt(14)
	v_mfma_f32_32x32x16_bf16 v[18:33], v[174:177], v[98:101], v[18:33]
	v_exp_f32_e32 v62, v62
	v_exp_f32_e32 v63, v63
	v_exp_f32_e32 v64, v64
	v_exp_f32_e32 v65, v65
	ds_read_b128 v[126:129], v78 offset:3584
	ds_read_b64 v[130:131], v79 offset:4352
	s_waitcnt lgkmcnt(14)
	v_mfma_f32_32x32x16_bf16 v[2:17], v[94:97], v[90:93], v[2:17]
	v_exp_f32_e32 v34, v34
	v_exp_f32_e32 v35, v35
	v_exp_f32_e32 v36, v36
	v_exp_f32_e32 v37, v37
	s_waitcnt lgkmcnt(12)
	v_mfma_f32_32x32x16_bf16 v[18:33], v[94:97], v[82:85], v[18:33]
	v_exp_f32_e32 v38, v38
	v_exp_f32_e32 v39, v39
	v_exp_f32_e32 v40, v40
	v_exp_f32_e32 v41, v41
	s_waitcnt lgkmcnt(10)
	v_mfma_f32_32x32x16_bf16 v[2:17], v[106:109], v[102:105], v[2:17]
	v_exp_f32_e32 v42, v42
	v_exp_f32_e32 v43, v43
	v_exp_f32_e32 v44, v44
	v_exp_f32_e32 v45, v45
	s_waitcnt lgkmcnt(8)
	v_mfma_f32_32x32x16_bf16 v[18:33], v[106:109], v[86:89], v[18:33]
	v_exp_f32_e32 v46, v46
	v_exp_f32_e32 v47, v47
	v_exp_f32_e32 v48, v48
	v_exp_f32_e32 v49, v49
	s_add_i32 s53, s13, 1
	s_cmp_lg_u32 s13, 2
	s_mov_b32 s52, s11
	s_cselect_b32 s11, s53, 0
	s_add_i32 s61, s61, 2
	s_waitcnt vmcnt(2) lgkmcnt(0)
	s_barrier
	s_addk_i32 s7, 0x80
	s_mov_b32 s62, s13
	s_cmpk_lt_u32 s61, 0x7f
	s_cbranch_scc1 .LBB0_65
; #define AF_WAIT_BAR(N) asm volatile("s_waitcnt vmcnt(" #N ") lgkmcnt(0)\n\ts_barrier" ::: "memory")
; #define AF_ROT() do { s_prev = s_cur; s_cur = s_next; s_next = (s_next == 2) ? 0 : s_next + 1; } while (0)
; #define AF_WAIT_BAR(N) asm volatile("s_waitcnt vmcnt(" #N ") lgkmcnt(0)\n\ts_barrier" ::: "memory")
; #define AF_ROT() do { s_prev = s_cur; s_cur = s_next; s_next = (s_next == 2) ? 0 : s_next + 1; } while (0)
; __device__ __forceinline__ void dense_unit(int b, int h, int qb, const bf16* Q, const bf16* __restrict__ KV, const char* __restrict__ K6N, const char* __restrict__ K6R, bf16* O, char* shm, const int tid) {
;     ...
;   AF_STEP(pB0, pB1, pA0, pA1, NT - 3, false, true, true);  AF_WAIT_BAR(1); AF_ROT();
	s_nop 0
	s_nop 0
	s_nop 0
	s_nop 0
	s_nop 0
	s_nop 0
	s_nop 0
	s_nop 0
	s_nop 0
	s_nop 0
	s_nop 0
	s_nop 0
	s_and_b32 s7, s55, 0x3fffffc0
	s_lshl_b32 s7, s7, 2
	s_add_i32 s8, s7, 0
	ds_read_b64_tr_b16 v[82:83], v157 offset:31744
	ds_read_b64_tr_b16 v[84:85], v157 offset:32256
	v_add_f32_e32 v78, v50, v51
	ds_read_b64_tr_b16 v[86:87], v157 offset:35840
	ds_read_b64_tr_b16 v[88:89], v157 offset:36352
	v_add_f32_e32 v78, v52, v78
	v_add_f32_e32 v78, v53, v78
	v_add_f32_e32 v78, v54, v78
	v_add_f32_e32 v78, v55, v78
	v_add_f32_e32 v78, v56, v78
	v_add_f32_e32 v78, v57, v78
	v_cvt_pk_bf16_f32 v50, v50, v51
	v_cvt_pk_bf16_f32 v51, v52, v53
	v_cvt_pk_bf16_f32 v52, v54, v55
	v_cvt_pk_bf16_f32 v53, v56, v57
	s_waitcnt lgkmcnt(10)
	v_mfma_scale_f32_32x32x64_f8f6f4 v[98:113], v[72:77], v[120:125], 0, v139, v0 op_sel_hi:[0,0,0] cbsz:2 blgp:2
	ds_read_b64_tr_b16 v[54:55], v157 offset:32768
	ds_read_b64_tr_b16 v[56:57], v157 offset:33280
	ds_read_b64_tr_b16 v[90:91], v157 offset:36864
	ds_read_b64_tr_b16 v[92:93], v157 offset:37376
	v_add_f32_e32 v72, v58, v78
	v_add_f32_e32 v72, v59, v72
	v_add_f32_e32 v72, v60, v72
	v_add_f32_e32 v72, v61, v72
	v_add_f32_e32 v72, v62, v72
	v_add_f32_e32 v94, v63, v72
	v_add_f32_e32 v94, v64, v94
	v_add_f32_e32 v145, v65, v94
	v_cvt_pk_bf16_f32 v58, v58, v59
	v_cvt_pk_bf16_f32 v59, v60, v61
	v_cvt_pk_bf16_f32 v60, v62, v63
	v_cvt_pk_bf16_f32 v61, v64, v65
	s_waitcnt lgkmcnt(12)
	v_mfma_scale_f32_32x32x64_f8f6f4 v[66:81], v[66:71], v[120:125], 0, v139, v0 op_sel_hi:[0,0,0] cbsz:2 blgp:2
	ds_read_b64_tr_b16 v[62:63], v157 offset:33792
	ds_read_b64_tr_b16 v[64:65], v157 offset:34304
	ds_read_b64_tr_b16 v[94:95], v157 offset:37888
	ds_read_b64_tr_b16 v[96:97], v157 offset:38400
	s_waitcnt lgkmcnt(14)
	v_mfma_scale_f32_32x32x64_f8f6f4 v[98:113], v[132:137], v[114:119], v[98:113], v139, v0 op_sel_hi:[0,0,0] cbsz:2 blgp:2
	v_add_f32_e32 v132, v34, v145
	v_add_f32_e32 v132, v35, v132
	v_add_f32_e32 v132, v36, v132
	v_add_f32_e32 v132, v37, v132
	v_add_f32_e32 v132, v38, v132
	v_add_f32_e32 v132, v39, v132
	v_add_f32_e32 v132, v40, v132
	v_add_f32_e32 v132, v41, v132
	v_cvt_pk_bf16_f32 v134, v34, v35
	v_cvt_pk_bf16_f32 v135, v36, v37
	v_cvt_pk_bf16_f32 v136, v38, v39
	v_cvt_pk_bf16_f32 v137, v40, v41
	ds_read_b64_tr_b16 v[174:175], v157 offset:34816
	ds_read_b64_tr_b16 v[176:177], v157 offset:35328
	ds_read_b64_tr_b16 v[178:179], v157 offset:38912
	ds_read_b64_tr_b16 v[180:181], v157 offset:39424
	v_add_f32_e32 v34, v42, v132
	v_add_f32_e32 v34, v43, v34
	v_add_f32_e32 v34, v44, v34
	v_add_f32_e32 v34, v45, v34
	v_add_f32_e32 v34, v46, v34
	v_add_f32_e32 v34, v47, v34
	v_add_f32_e32 v34, v48, v34
	s_waitcnt lgkmcnt(14)
	v_mfma_scale_f32_32x32x64_f8f6f4 v[66:81], v[126:131], v[114:119], v[66:81], v139, v0 op_sel_hi:[0,0,0] cbsz:2 blgp:2
	v_add_f32_e32 v126, v49, v34
	v_cvt_pk_bf16_f32 v182, v42, v43
	v_cvt_pk_bf16_f32 v183, v44, v45
	v_cvt_pk_bf16_f32 v184, v46, v47
	v_cvt_pk_bf16_f32 v185, v48, v49
	s_or_b32 s52, s6, 0x1f80
	s_ashr_i32 s53, s52, 31
	s_lshl_b64 s[52:53], s[52:53], 12
	s_add_u32 s52, s1, s52
	s_addc_u32 s53, s54, s53
	s_mov_b32 s7, m0
	s_mov_b32 m0, s12
	s_nop 0
	global_load_lds_dwordx4 v141, s[52:53]
	s_mov_b32 m0, s7
	v_mfma_f32_32x32x16_bf16 v[2:17], v[50:53], v[82:85], v[2:17]
	v_exp_f32_e32 v98, v98
	v_exp_f32_e32 v99, v99
	v_exp_f32_e32 v100, v100
	v_exp_f32_e32 v101, v101
	ds_read_b128 v[34:37], v154 offset:5120
	ds_read_b64 v[38:39], v155 offset:7168
	s_waitcnt lgkmcnt(14)
	v_mfma_f32_32x32x16_bf16 v[18:33], v[50:53], v[86:89], v[18:33]
	v_exp_f32_e32 v102, v102
	v_exp_f32_e32 v103, v103
	v_exp_f32_e32 v104, v104
	v_exp_f32_e32 v105, v105
	ds_read_b128 v[40:43], v154 offset:5632
	ds_read_b64 v[44:45], v155 offset:7424
	s_waitcnt lgkmcnt(14)
	v_mfma_f32_32x32x16_bf16 v[2:17], v[58:61], v[54:57], v[2:17]
	v_exp_f32_e32 v106, v106
	v_exp_f32_e32 v107, v107
	v_exp_f32_e32 v108, v108
	v_exp_f32_e32 v109, v109
	ds_read_b128 v[128:131], v154 offset:8192
	ds_read_b64 v[132:133], v155 offset:9216
	s_waitcnt lgkmcnt(14)
	v_mfma_f32_32x32x16_bf16 v[18:33], v[58:61], v[90:93], v[18:33]
	v_exp_f32_e32 v110, v110
	v_exp_f32_e32 v111, v111
	v_exp_f32_e32 v112, v112
	v_exp_f32_e32 v113, v113
	ds_read_b128 v[164:167], v154 offset:8704
	ds_read_b64 v[168:169], v155 offset:9472
	s_waitcnt lgkmcnt(14)
	v_mfma_f32_32x32x16_bf16 v[2:17], v[134:137], v[62:65], v[2:17]
	v_exp_f32_e32 v66, v66
	v_exp_f32_e32 v67, v67
	v_exp_f32_e32 v68, v68
	v_exp_f32_e32 v69, v69
	s_waitcnt lgkmcnt(12)
	v_mfma_f32_32x32x16_bf16 v[18:33], v[134:137], v[94:97], v[18:33]
	v_exp_f32_e32 v70, v70
	v_exp_f32_e32 v71, v71
	v_exp_f32_e32 v72, v72
	v_exp_f32_e32 v73, v73
	s_waitcnt lgkmcnt(10)
	v_mfma_f32_32x32x16_bf16 v[2:17], v[182:185], v[174:177], v[2:17]
	v_exp_f32_e32 v74, v74
	v_exp_f32_e32 v75, v75
	v_exp_f32_e32 v76, v76
	v_exp_f32_e32 v77, v77
	s_waitcnt lgkmcnt(8)
	v_mfma_f32_32x32x16_bf16 v[18:33], v[182:185], v[178:181], v[18:33]
	v_exp_f32_e32 v78, v78
	v_exp_f32_e32 v79, v79
	v_exp_f32_e32 v80, v80
	v_exp_f32_e32 v81, v81
	s_waitcnt vmcnt(1) lgkmcnt(0)
	s_barrier
; #define AF_WAIT_BAR(N) asm volatile("s_waitcnt vmcnt(" #N ") lgkmcnt(0)\n\ts_barrier" ::: "memory")
; #define AF_ROT() do { s_prev = s_cur; s_cur = s_next; s_next = (s_next == 2) ? 0 : s_next + 1; } while (0)
; #define AF_WAIT_BAR(N) asm volatile("s_waitcnt vmcnt(" #N ") lgkmcnt(0)\n\ts_barrier" ::: "memory")
; #define AF_ROT() do { s_prev = s_cur; s_cur = s_next; s_next = (s_next == 2) ? 0 : s_next + 1; } while (0)
; __device__ __forceinline__ void dense_unit(int b, int h, int qb, const bf16* Q, const bf16* __restrict__ KV, const char* __restrict__ K6N, const char* __restrict__ K6R, bf16* O, char* shm, const int tid) {
;     ...
;   AF_STEP(pA0, pA1, pB0, pB1, NT - 2, false, true, true);  AF_WAIT_BAR(0); AF_ROT();
	ds_read_b64_tr_b16 v[46:47], v157 offset:15360
	ds_read_b64_tr_b16 v[48:49], v157 offset:15872
	v_add_f32_e32 v50, v98, v99
	ds_read_b64_tr_b16 v[134:135], v157 offset:19456
	ds_read_b64_tr_b16 v[136:137], v157 offset:19968
	v_add_f32_e32 v50, v100, v50
	v_add_f32_e32 v50, v101, v50
	v_add_f32_e32 v50, v102, v50
	v_add_f32_e32 v50, v103, v50
	v_add_f32_e32 v50, v104, v50
	v_add_f32_e32 v50, v105, v50
	v_cvt_pk_bf16_f32 v174, v98, v99
	v_cvt_pk_bf16_f32 v175, v100, v101
	v_cvt_pk_bf16_f32 v176, v102, v103
	v_cvt_pk_bf16_f32 v177, v104, v105
	s_waitcnt lgkmcnt(10)
	v_mfma_scale_f32_32x32x64_f8f6f4 v[82:97], v[34:39], v[120:125], 0, v139, v0 op_sel_hi:[0,0,0] cbsz:2 blgp:2
	ds_read_b64_tr_b16 v[100:101], v157 offset:16384
	ds_read_b64_tr_b16 v[102:103], v157 offset:16896
	ds_read_b64_tr_b16 v[178:179], v157 offset:20480
	ds_read_b64_tr_b16 v[180:181], v157 offset:20992
	v_add_f32_e32 v34, v106, v50
	v_add_f32_e32 v34, v107, v34
	v_add_f32_e32 v34, v108, v34
	v_add_f32_e32 v34, v109, v34
	v_add_f32_e32 v34, v110, v34
	v_add_f32_e32 v34, v111, v34
	v_add_f32_e32 v34, v112, v34
	v_add_f32_e32 v34, v113, v34
	v_cvt_pk_bf16_f32 v106, v106, v107
	v_cvt_pk_bf16_f32 v107, v108, v109
	v_cvt_pk_bf16_f32 v108, v110, v111
	v_cvt_pk_bf16_f32 v109, v112, v113
	s_waitcnt lgkmcnt(12)
	v_mfma_scale_f32_32x32x64_f8f6f4 v[50:65], v[40:45], v[120:125], 0, v139, v0 op_sel_hi:[0,0,0] cbsz:2 blgp:2
	ds_read_b64_tr_b16 v[182:183], v157 offset:17408
	ds_read_b64_tr_b16 v[184:185], v157 offset:17920
	ds_read_b64_tr_b16 v[204:205], v157 offset:21504
	ds_read_b64_tr_b16 v[206:207], v157 offset:22016
	v_add_f32_e32 v34, v66, v34
	v_add_f32_e32 v34, v67, v34
	v_add_f32_e32 v34, v68, v34
	v_add_f32_e32 v34, v69, v34
	v_add_f32_e32 v34, v70, v34
	v_add_f32_e32 v34, v71, v34
	v_add_f32_e32 v34, v72, v34
	v_add_f32_e32 v34, v73, v34
	v_cvt_pk_bf16_f32 v66, v66, v67
	v_cvt_pk_bf16_f32 v67, v68, v69
	v_cvt_pk_bf16_f32 v68, v70, v71
	v_cvt_pk_bf16_f32 v69, v72, v73
	s_waitcnt lgkmcnt(14)
	v_mfma_scale_f32_32x32x64_f8f6f4 v[82:97], v[128:133], v[114:119], v[82:97], v139, v0 op_sel_hi:[0,0,0] cbsz:2 blgp:2
	ds_read_b64_tr_b16 v[70:71], v157 offset:18432
	ds_read_b64_tr_b16 v[72:73], v157 offset:18944
	ds_read_b64_tr_b16 v[128:129], v157 offset:22528
	ds_read_b64_tr_b16 v[130:131], v157 offset:23040
	v_add_f32_e32 v34, v74, v34
	v_add_f32_e32 v34, v75, v34
	v_add_f32_e32 v34, v76, v34
	v_add_f32_e32 v34, v77, v34
	v_add_f32_e32 v34, v78, v34
	v_add_f32_e32 v34, v79, v34
	v_add_f32_e32 v34, v80, v34
	v_add_f32_e32 v98, v81, v34
	v_cvt_pk_bf16_f32 v74, v74, v75
	v_cvt_pk_bf16_f32 v75, v76, v77
	v_cvt_pk_bf16_f32 v76, v78, v79
	v_cvt_pk_bf16_f32 v77, v80, v81
	s_waitcnt lgkmcnt(14)
	v_mfma_scale_f32_32x32x64_f8f6f4 v[50:65], v[164:169], v[114:119], v[50:65], v139, v0 op_sel_hi:[0,0,0] cbsz:2 blgp:2
	s_or_b32 s6, s6, 0x1fc0
	s_ashr_i32 s7, s6, 31
	s_lshl_b64 s[6:7], s[6:7], 12
	s_add_u32 s6, s1, s6
	s_addc_u32 s7, s54, s7
	s_mov_b32 s1, m0
	s_mov_b32 m0, s10
	s_nop 0
	global_load_lds_dwordx4 v141, s[6:7]
	s_mov_b32 m0, s1
	v_mfma_f32_32x32x16_bf16 v[2:17], v[174:177], v[46:49], v[2:17]
	v_exp_f32_e32 v82, v82
	v_exp_f32_e32 v83, v83
	v_exp_f32_e32 v84, v84
	v_exp_f32_e32 v85, v85
	ds_read_b128 v[34:37], v154 offset:10240
	ds_read_b64 v[38:39], v155 offset:12288
	s_waitcnt lgkmcnt(14)
	v_mfma_f32_32x32x16_bf16 v[18:33], v[174:177], v[134:137], v[18:33]
	v_exp_f32_e32 v86, v86
	v_exp_f32_e32 v87, v87
	v_exp_f32_e32 v88, v88
	v_exp_f32_e32 v89, v89
	ds_read_b128 v[40:43], v154 offset:10752
	ds_read_b64 v[44:45], v155 offset:12544
	s_waitcnt lgkmcnt(14)
	v_mfma_f32_32x32x16_bf16 v[2:17], v[106:109], v[100:103], v[2:17]
	v_exp_f32_e32 v90, v90
	v_exp_f32_e32 v91, v91
	v_exp_f32_e32 v92, v92
	v_exp_f32_e32 v93, v93
	ds_read_b128 v[100:103], v154 offset:13312
	ds_read_b64 v[104:105], v155 offset:14336
	s_waitcnt lgkmcnt(14)
	v_mfma_f32_32x32x16_bf16 v[18:33], v[106:109], v[178:181], v[18:33]
	v_exp_f32_e32 v94, v94
	v_exp_f32_e32 v95, v95
	v_exp_f32_e32 v96, v96
	v_exp_f32_e32 v97, v97
	ds_read_b128 v[106:109], v154 offset:13824
	ds_read_b64 v[110:111], v155 offset:14592
	s_waitcnt lgkmcnt(14)
	v_mfma_f32_32x32x16_bf16 v[2:17], v[66:69], v[182:185], v[2:17]
	v_exp_f32_e32 v50, v50
	v_exp_f32_e32 v51, v51
	v_exp_f32_e32 v52, v52
	v_exp_f32_e32 v53, v53
	s_waitcnt lgkmcnt(12)
	v_mfma_f32_32x32x16_bf16 v[18:33], v[66:69], v[204:207], v[18:33]
	v_exp_f32_e32 v54, v54
	v_exp_f32_e32 v55, v55
	v_exp_f32_e32 v56, v56
	v_exp_f32_e32 v57, v57
	s_waitcnt lgkmcnt(10)
	v_mfma_f32_32x32x16_bf16 v[2:17], v[74:77], v[70:73], v[2:17]
	v_exp_f32_e32 v58, v58
	v_exp_f32_e32 v59, v59
	v_exp_f32_e32 v60, v60
	v_exp_f32_e32 v61, v61
	s_waitcnt lgkmcnt(8)
	v_mfma_f32_32x32x16_bf16 v[18:33], v[74:77], v[128:131], v[18:33]
	v_exp_f32_e32 v62, v62
	v_exp_f32_e32 v63, v63
	v_exp_f32_e32 v64, v64
	v_exp_f32_e32 v65, v65
	s_waitcnt vmcnt(0) lgkmcnt(0)
	s_barrier
; #define AF_SBAR() __builtin_amdgcn_sched_barrier(0)
; __device__ __forceinline__ s16x4 vtr(lds_cptr p) { return __builtin_bit_cast(s16x4, __builtin_amdgcn_ds_read_tr16_b64_v4i16((__attribute__((address_space(3))) v4i16_t*)p)); }
; #define AF_MF(a, b, c) __builtin_amdgcn_mfma_f32_32x32x16_bf16(a, b, c, 0, 0, 0)
; #define AF_PKW(P, B) cvtpk_s(P[B], P[B + 1])
; #define AF_SBAR() __builtin_amdgcn_sched_barrier(0)
; __device__ __forceinline__ s16x4 vtr(lds_cptr p) { return __builtin_bit_cast(s16x4, __builtin_amdgcn_ds_read_tr16_b64_v4i16((__attribute__((address_space(3))) v4i16_t*)p)); }
; #define AF_PKW(P, B) cvtpk_s(P[B], P[B + 1])
; #define AF_MF(a, b, c) __builtin_amdgcn_mfma_f32_32x32x16_bf16(a, b, c, 0, 0, 0)
; __device__ __forceinline__ void dense_unit(int b, int h, int qb, const bf16* Q, const bf16* __restrict__ KV, const char* __restrict__ K6N, const char* __restrict__ K6R, bf16* O, char* shm, const int tid) {
;     ...
;   AF_STEP(pB0, pB1, pA0, pA1, NT - 1, false, false, false);
;   { float sacc = pB0[0] + pB0[1];
; #pragma unroll
;     for (int r = 2; r < 16; ++r) sacc += pB0[r];
; #pragma unroll
;     for (int r = 0; r < 16; ++r) sacc += pB1[r];
;     l_reg += sacc;
;     pw0 = (u32x4){AF_PKW(pB0, 0), AF_PKW(pB0, 2), AF_PKW(pB0, 4), AF_PKW(pB0, 6)}; pw1 = (u32x4){AF_PKW(pB0, 8), AF_PKW(pB0, 10), AF_PKW(pB0, 12), AF_PKW(pB0, 14)};
;     pw2 = (u32x4){AF_PKW(pB1, 0), AF_PKW(pB1, 2), AF_PKW(pB1, 4), AF_PKW(pB1, 6)}; pw3 = (u32x4){AF_PKW(pB1, 8), AF_PKW(pB1, 10), AF_PKW(pB1, 12), AF_PKW(pB1, 14)};
;     AF_SBAR();
;     const lds_cptr vp_ = vp0 + s_cur * VSLOT;
; #pragma unroll
;     for (int i = 0; i < 8; ++i) { vlo[i] = vtr(vp_ + ((i >> 2) * 4096 + (i & 3) * 1024)); vhi[i] = vtr(vp_ + ((i >> 2) * 4096 + (i & 3) * 1024 + 512)); }
;     o[0] = AF_MF(AF_PAF(0), AF_VFR(0), o[0]); o[1] = AF_MF(AF_PAF(0), AF_VFR(4), o[1]);
	ds_read_b64_tr_b16 v[128:129], v157 offset:23552
	ds_read_b64_tr_b16 v[130:131], v157 offset:24064
	v_add_f32_e32 v46, v82, v83
	ds_read_b64_tr_b16 v[132:133], v157 offset:27648
	ds_read_b64_tr_b16 v[134:135], v157 offset:28160
	v_add_f32_e32 v46, v84, v46
	v_add_f32_e32 v46, v85, v46
	v_add_f32_e32 v46, v86, v46
	v_add_f32_e32 v46, v87, v46
	v_add_f32_e32 v46, v88, v46
	v_add_f32_e32 v46, v89, v46
	v_cvt_pk_bf16_f32 v82, v82, v83
	v_cvt_pk_bf16_f32 v83, v84, v85
	v_cvt_pk_bf16_f32 v84, v86, v87
	v_cvt_pk_bf16_f32 v85, v88, v89
	s_waitcnt lgkmcnt(10)
	v_mfma_scale_f32_32x32x64_f8f6f4 v[66:81], v[34:39], v[120:125], 0, v139, v0 op_sel_hi:[0,0,0] cbsz:2 blgp:2
	ds_read_b64_tr_b16 v[86:87], v157 offset:24576
	ds_read_b64_tr_b16 v[88:89], v157 offset:25088
	ds_read_b64_tr_b16 v[164:165], v157 offset:28672
	ds_read_b64_tr_b16 v[166:167], v157 offset:29184
	v_add_f32_e32 v34, v90, v46
	v_add_f32_e32 v34, v91, v34
	v_add_f32_e32 v34, v92, v34
	v_add_f32_e32 v34, v93, v34
	v_add_f32_e32 v34, v94, v34
	v_add_f32_e32 v99, v95, v34
	s_waitcnt lgkmcnt(12)
	v_mfma_scale_f32_32x32x64_f8f6f4 v[34:49], v[40:45], v[120:125], 0, v139, v0 op_sel_hi:[0,0,0] cbsz:2 blgp:2
	v_add_f32_e32 v99, v96, v99
	v_add_f32_e32 v99, v97, v99
	v_cvt_pk_bf16_f32 v90, v90, v91
	v_cvt_pk_bf16_f32 v91, v92, v93
	v_cvt_pk_bf16_f32 v92, v94, v95
	v_cvt_pk_bf16_f32 v93, v96, v97
	ds_read_b64_tr_b16 v[94:95], v157 offset:25600
	ds_read_b64_tr_b16 v[96:97], v157 offset:26112
	ds_read_b64_tr_b16 v[120:121], v157 offset:29696
	ds_read_b64_tr_b16 v[122:123], v157 offset:30208
	v_add_f32_e32 v99, v50, v99
	v_add_f32_e32 v99, v51, v99
	v_add_f32_e32 v99, v52, v99
	v_add_f32_e32 v99, v53, v99
	v_add_f32_e32 v99, v54, v99
	v_add_f32_e32 v99, v55, v99
	v_add_f32_e32 v99, v56, v99
	v_add_f32_e32 v99, v57, v99
	v_cvt_pk_bf16_f32 v50, v50, v51
	v_cvt_pk_bf16_f32 v51, v52, v53
	v_cvt_pk_bf16_f32 v52, v54, v55
	v_cvt_pk_bf16_f32 v53, v56, v57
	s_waitcnt lgkmcnt(14)
	v_mfma_scale_f32_32x32x64_f8f6f4 v[66:81], v[100:105], v[114:119], v[66:81], v139, v0 op_sel_hi:[0,0,0] cbsz:2 blgp:2
	ds_read_b64_tr_b16 v[54:55], v157 offset:26624
	ds_read_b64_tr_b16 v[56:57], v157 offset:27136
	ds_read_b64_tr_b16 v[100:101], v157 offset:30720
	ds_read_b64_tr_b16 v[102:103], v157 offset:31232
	s_waitcnt lgkmcnt(14)
	v_mfma_scale_f32_32x32x64_f8f6f4 v[34:49], v[106:111], v[114:119], v[34:49], v139, v0 op_sel_hi:[0,0,0] cbsz:2 blgp:2
	v_add_f32_e32 v0, v58, v99
	v_add_f32_e32 v0, v59, v0
	v_add_f32_e32 v0, v60, v0
	v_add_f32_e32 v0, v61, v0
	v_add_f32_e32 v0, v62, v0
	v_add_f32_e32 v0, v63, v0
	v_add_f32_e32 v0, v64, v0
	v_add_f32_e32 v0, v65, v0
	v_cvt_pk_bf16_f32 v58, v58, v59
	v_cvt_pk_bf16_f32 v59, v60, v61
	v_cvt_pk_bf16_f32 v60, v62, v63
	v_cvt_pk_bf16_f32 v61, v64, v65
	v_mfma_f32_32x32x16_bf16 v[2:17], v[82:85], v[128:131], v[2:17]
	v_exp_f32_e32 v66, v66
	v_exp_f32_e32 v67, v67
	v_exp_f32_e32 v68, v68
	v_exp_f32_e32 v69, v69
	s_waitcnt lgkmcnt(12)
	v_mfma_f32_32x32x16_bf16 v[18:33], v[82:85], v[132:135], v[18:33]
	v_exp_f32_e32 v70, v70
	v_exp_f32_e32 v71, v71
	v_exp_f32_e32 v72, v72
	v_exp_f32_e32 v73, v73
	s_waitcnt lgkmcnt(10)
	v_mfma_f32_32x32x16_bf16 v[2:17], v[90:93], v[86:89], v[2:17]
	v_exp_f32_e32 v74, v74
	v_exp_f32_e32 v75, v75
	v_exp_f32_e32 v76, v76
	v_exp_f32_e32 v77, v77
	s_waitcnt lgkmcnt(8)
	v_mfma_f32_32x32x16_bf16 v[18:33], v[90:93], v[164:167], v[18:33]
	v_exp_f32_e32 v78, v78
	v_exp_f32_e32 v79, v79
	v_exp_f32_e32 v80, v80
	v_exp_f32_e32 v81, v81
	s_waitcnt lgkmcnt(6)
	v_mfma_f32_32x32x16_bf16 v[2:17], v[50:53], v[94:97], v[2:17]
	v_exp_f32_e32 v34, v34
	v_exp_f32_e32 v35, v35
	v_exp_f32_e32 v36, v36
	v_exp_f32_e32 v37, v37
	s_waitcnt lgkmcnt(4)
	v_mfma_f32_32x32x16_bf16 v[18:33], v[50:53], v[120:123], v[18:33]
	v_exp_f32_e32 v38, v38
	v_exp_f32_e32 v39, v39
	v_exp_f32_e32 v40, v40
	v_exp_f32_e32 v41, v41
	s_waitcnt lgkmcnt(2)
	v_mfma_f32_32x32x16_bf16 v[2:17], v[58:61], v[54:57], v[2:17]
	v_exp_f32_e32 v42, v42
	v_exp_f32_e32 v43, v43
	v_exp_f32_e32 v44, v44
	v_exp_f32_e32 v45, v45
	s_waitcnt lgkmcnt(0)
	v_mfma_f32_32x32x16_bf16 v[18:33], v[58:61], v[100:103], v[18:33]
	v_exp_f32_e32 v46, v46
	v_exp_f32_e32 v47, v47
	v_exp_f32_e32 v48, v48
	v_exp_f32_e32 v49, v49
	v_add_f32_e32 v50, v66, v67
	v_add_f32_e32 v50, v68, v50
	v_add_f32_e32 v50, v69, v50
	v_add_f32_e32 v50, v70, v50
	v_add_f32_e32 v50, v71, v50
	v_add_f32_e32 v50, v72, v50
	v_add_f32_e32 v50, v73, v50
	v_add_f32_e32 v50, v74, v50
	v_add_f32_e32 v50, v75, v50
	v_add_f32_e32 v50, v76, v50
	v_add_f32_e32 v50, v77, v50
	v_add_f32_e32 v50, v78, v50
	v_add_f32_e32 v50, v79, v50
	v_add_f32_e32 v50, v80, v50
	v_add_f32_e32 v82, v81, v50
	v_add_f32_e32 v50, v143, v126
	v_add_f32_e32 v50, v50, v98
	v_add_f32_e32 v0, v50, v0
	v_cvt_pk_bf16_f32 v50, v66, v67
	v_cvt_pk_bf16_f32 v51, v68, v69
	v_cvt_pk_bf16_f32 v52, v70, v71
	v_cvt_pk_bf16_f32 v53, v72, v73
	v_cvt_pk_bf16_f32 v54, v74, v75
	v_cvt_pk_bf16_f32 v55, v76, v77
	v_cvt_pk_bf16_f32 v56, v78, v79
	v_cvt_pk_bf16_f32 v57, v80, v81
	v_cvt_pk_bf16_f32 v58, v34, v35
	v_cvt_pk_bf16_f32 v59, v36, v37
	v_cvt_pk_bf16_f32 v60, v38, v39
	v_cvt_pk_bf16_f32 v61, v40, v41
	v_cvt_pk_bf16_f32 v62, v42, v43
	v_cvt_pk_bf16_f32 v63, v44, v45
	v_cvt_pk_bf16_f32 v64, v46, v47
	v_cvt_pk_bf16_f32 v65, v48, v49
	ds_read_b64_tr_b16 v[66:67], v157 offset:31744
	ds_read_b64_tr_b16 v[68:69], v157 offset:32256
	v_add_f32_e32 v34, v34, v82
	v_add_f32_e32 v34, v35, v34
	v_add_f32_e32 v34, v36, v34
	v_add_f32_e32 v34, v37, v34
	s_waitcnt lgkmcnt(0)
; __device__ __forceinline__ int crow(int r, int hi) { return (r & 3) + 8 * (r >> 2) + 4 * hi; }
;   __device__ __forceinline__ bf16* orow(int wid, int row) const { return O + (long)(8192 * b + qpos0(wid) + row) * 1024 + 64 * head(wid); }
;   __device__ __forceinline__ bf16* orow(int wid, int row) const { return O + (long)(8192 * b + 64 * qrow(wid) + 32 * (wid & 1) + row) * 1024 + 512 + 64 * h; }
; __device__ __forceinline__ int crow(int r, int hi) { return (r & 3) + 8 * (r >> 2) + 4 * hi; }
; __device__ __forceinline__ unsigned cvtpk_s(float lo, float hi) { f32x2_t v = {lo, hi}; bf16x2_t b = __builtin_convertvector(v, bf16x2_t); return __builtin_bit_cast(unsigned, b); }
; __device__ __forceinline__ void dense_unit(int b, int h, int qb, const bf16* Q, const bf16* __restrict__ KV, const char* __restrict__ K6N, const char* __restrict__ K6R, bf16* O, char* shm, const int tid) {
;     ...
;     o[0] = AF_MF(AF_PAF(0), AF_VFR(0), o[0]); o[1] = AF_MF(AF_PAF(0), AF_VFR(4), o[1]);
;     o[0] = AF_MF(AF_PAF(1), AF_VFR(1), o[0]); o[1] = AF_MF(AF_PAF(1), AF_VFR(5), o[1]);
;     o[0] = AF_MF(AF_PAF(2), AF_VFR(2), o[0]); o[1] = AF_MF(AF_PAF(2), AF_VFR(6), o[1]);
;     o[0] = AF_MF(AF_PAF(3), AF_VFR(3), o[0]); o[1] = AF_MF(AF_PAF(3), AF_VFR(7), o[1]); }
;   { auto rr = __builtin_amdgcn_permlane32_swap(__float_as_uint(l_reg), __float_as_uint(l_reg), false, false); l_reg = __uint_as_float(rr[0]) + __uint_as_float(rr[1]); }
;   if (hi == 0) wsf[32 + r32] = l_reg; asm volatile("s_waitcnt lgkmcnt(0)" ::: "memory");
;   float rli[16];
; #pragma unroll
;   for (int r = 0; r < 16; ++r) rli[r] = __builtin_amdgcn_rcpf(wsf[32 + crow(r, hi)]);
;   bf16* Ow = O + (long)(8192 * b + 256 * qb + 32 * wid) * 1024 + 64 * h;
;   { bf16* stg = (bf16*)(shm + LDS_OST) + wid * 2048;
; #pragma unroll
;     for (int r = 0; r < 16; ++r) { const int orow = crow(r, hi);
; #pragma unroll
;       for (int d0 = 0; d0 < 2; ++d0) stg[orow * 64 + d0 * 32 + r32] = (bf16)(cvtpk_s(o[d0][r] * rli[r], 0.f) & 0xffffu); }
;     asm volatile("s_waitcnt lgkmcnt(0)" ::: "memory");
; #pragma unroll
;     for (int i = 0; i < 4; ++i) { const int row = i * 8 + (lane >> 3), ch = lane & 7; const u32x4 v = *(const u32x4*)(stg + row * 64 + ch * 8); *(u32x4*)(Ow + (long)row * 1024 + ch * 8) = v; } }
;   asm volatile("s_waitcnt lgkmcnt(0)\n\ts_barrier" ::: "memory");
	v_mfma_f32_32x32x16_bf16 v[2:17], v[50:53], v[66:69], v[2:17]
	ds_read_b64_tr_b16 v[66:67], v157 offset:35840
	ds_read_b64_tr_b16 v[68:69], v157 offset:36352
	v_add_f32_e32 v34, v38, v34
	v_add_f32_e32 v34, v39, v34
	v_add_f32_e32 v34, v40, v34
	v_add_f32_e32 v34, v41, v34
	v_add_f32_e32 v34, v42, v34
	v_add_f32_e32 v34, v43, v34
	s_waitcnt lgkmcnt(0)
	v_mfma_f32_32x32x16_bf16 v[18:33], v[50:53], v[66:69], v[18:33]
	ds_read_b64_tr_b16 v[50:51], v157 offset:32768
	ds_read_b64_tr_b16 v[52:53], v157 offset:33280
	v_add_f32_e32 v34, v44, v34
	v_add_f32_e32 v34, v45, v34
	v_add_f32_e32 v34, v46, v34
	v_add_f32_e32 v34, v47, v34
	v_add_f32_e32 v34, v48, v34
	v_add_f32_e32 v34, v49, v34
	s_waitcnt lgkmcnt(0)
	v_mfma_f32_32x32x16_bf16 v[2:17], v[54:57], v[50:53], v[2:17]
	ds_read_b64_tr_b16 v[50:51], v157 offset:36864
	ds_read_b64_tr_b16 v[52:53], v157 offset:37376
	v_add_f32_e32 v0, v0, v34
	v_mov_b32_e32 v34, v0
	s_nop 1
	v_permlane32_swap_b32_e32 v0, v34
	s_waitcnt lgkmcnt(0)
	v_mfma_f32_32x32x16_bf16 v[18:33], v[54:57], v[50:53], v[18:33]
	ds_read_b64_tr_b16 v[52:53], v157 offset:39424
	ds_read_b64_tr_b16 v[54:55], v157 offset:33792
	ds_read_b64_tr_b16 v[56:57], v157 offset:34304
	ds_read_b64_tr_b16 v[66:67], v157 offset:37888
	ds_read_b64_tr_b16 v[68:69], v157 offset:38400
	ds_read_b64_tr_b16 v[70:71], v157 offset:34816
	ds_read_b64_tr_b16 v[72:73], v157 offset:35328
	ds_read_b64_tr_b16 v[50:51], v157 offset:38912
	s_waitcnt lgkmcnt(5)
	v_mfma_f32_32x32x16_bf16 v[2:17], v[58:61], v[54:57], v[2:17]
	s_waitcnt lgkmcnt(3)
	v_mfma_f32_32x32x16_bf16 v[18:33], v[58:61], v[66:69], v[18:33]
	s_waitcnt lgkmcnt(1)
	v_mfma_f32_32x32x16_bf16 v[2:17], v[62:65], v[70:73], v[2:17]
	s_waitcnt lgkmcnt(0)
	v_mfma_f32_32x32x16_bf16 v[18:33], v[62:65], v[50:53], v[18:33]
	s_and_saveexec_b64 s[6:7], s[4:5]
	v_lshl_add_u32 v35, v150, 2, s8
	v_add_f32_e32 v0, v0, v34
	ds_write_b32 v35, v0 offset:40064
	s_or_b64 exec, exec, s[6:7]
	s_waitcnt lgkmcnt(0)
	v_add_u32_e32 v0, s8, v158
	ds_read_b128 v[34:37], v0 offset:40064
	ds_read_b128 v[38:41], v0 offset:40096
	s_ashr_i32 s1, s0, 31
	s_lshl_b64 s[0:1], s[0:1], 11
	s_add_u32 s0, s18, s0
	s_waitcnt lgkmcnt(1)
	v_rcp_f32_e32 v42, v34
	v_rcp_f32_e32 v43, v35
	v_rcp_f32_e32 v44, v36
	v_rcp_f32_e32 v45, v37
	s_waitcnt lgkmcnt(0)
	v_rcp_f32_e32 v46, v38
	ds_read_b128 v[34:37], v0 offset:40128
	v_rcp_f32_e32 v47, v39
	v_rcp_f32_e32 v48, v40
	v_rcp_f32_e32 v49, v41
	ds_read_b128 v[38:41], v0 offset:40160
	s_addc_u32 s1, s19, s1
	s_lshl_b32 s6, s41, 12
	s_waitcnt lgkmcnt(1)
	v_rcp_f32_e32 v0, v34
	v_rcp_f32_e32 v34, v35
	v_rcp_f32_e32 v35, v36
	v_rcp_f32_e32 v36, v37
	s_waitcnt lgkmcnt(0)
	v_rcp_f32_e32 v37, v38
	v_rcp_f32_e32 v38, v39
	v_rcp_f32_e32 v39, v40
	v_rcp_f32_e32 v40, v41
	s_add_i32 s6, s6, 0
	v_mul_f32_e32 v2, v2, v42
	v_lshlrev_b32_e32 v41, 1, v156
	v_lshlrev_b32_e32 v50, 1, v150
	v_cvt_pk_bf16_f32 v2, v2, s0
	v_add3_u32 v41, s6, v41, v50
	ds_write_b16 v41, v2 offset:41984
	v_mul_f32_e32 v2, v18, v42
	v_cvt_pk_bf16_f32 v2, v2, s0
	ds_write_b16 v41, v2 offset:42048
	v_mul_f32_e32 v2, v3, v43
	v_cvt_pk_bf16_f32 v2, v2, s0
	ds_write_b16 v41, v2 offset:42112
	v_mul_f32_e32 v2, v19, v43
	v_cvt_pk_bf16_f32 v2, v2, s0
	ds_write_b16 v41, v2 offset:42176
	v_mul_f32_e32 v2, v4, v44
	v_cvt_pk_bf16_f32 v2, v2, s0
	ds_write_b16 v41, v2 offset:42240
	v_mul_f32_e32 v2, v20, v44
	v_cvt_pk_bf16_f32 v2, v2, s0
	ds_write_b16 v41, v2 offset:42304
	v_mul_f32_e32 v2, v5, v45
	v_cvt_pk_bf16_f32 v2, v2, s0
	ds_write_b16 v41, v2 offset:42368
	v_mul_f32_e32 v2, v21, v45
	v_cvt_pk_bf16_f32 v2, v2, s0
	ds_write_b16 v41, v2 offset:42432
	v_mul_f32_e32 v2, v6, v46
	v_cvt_pk_bf16_f32 v2, v2, s0
	ds_write_b16 v41, v2 offset:43008
	v_mul_f32_e32 v2, v22, v46
	v_cvt_pk_bf16_f32 v2, v2, s0
	ds_write_b16 v41, v2 offset:43072
	v_mul_f32_e32 v2, v7, v47
	v_cvt_pk_bf16_f32 v2, v2, s0
	ds_write_b16 v41, v2 offset:43136
	v_mul_f32_e32 v2, v23, v47
	v_cvt_pk_bf16_f32 v2, v2, s0
	ds_write_b16 v41, v2 offset:43200
	v_mul_f32_e32 v2, v8, v48
	v_cvt_pk_bf16_f32 v2, v2, s0
	ds_write_b16 v41, v2 offset:43264
	v_mul_f32_e32 v2, v24, v48
	v_cvt_pk_bf16_f32 v2, v2, s0
	ds_write_b16 v41, v2 offset:43328
	v_mul_f32_e32 v2, v9, v49
	v_cvt_pk_bf16_f32 v2, v2, s0
	ds_write_b16 v41, v2 offset:43392
	v_mul_f32_e32 v2, v25, v49
	v_cvt_pk_bf16_f32 v2, v2, s0
	ds_write_b16 v41, v2 offset:43456
	v_mul_f32_e32 v2, v10, v0
	v_mul_f32_e32 v0, v26, v0
	v_cvt_pk_bf16_f32 v0, v0, s0
	ds_write_b16 v41, v0 offset:44096
	v_mul_f32_e32 v0, v11, v34
	v_cvt_pk_bf16_f32 v0, v0, s0
	ds_write_b16 v41, v0 offset:44160
	v_mul_f32_e32 v0, v27, v34
	v_cvt_pk_bf16_f32 v0, v0, s0
	ds_write_b16 v41, v0 offset:44224
	v_mul_f32_e32 v0, v12, v35
	v_cvt_pk_bf16_f32 v0, v0, s0
	ds_write_b16 v41, v0 offset:44288
	v_mul_f32_e32 v0, v28, v35
	v_cvt_pk_bf16_f32 v0, v0, s0
	ds_write_b16 v41, v0 offset:44352
	v_mul_f32_e32 v0, v13, v36
	v_cvt_pk_bf16_f32 v0, v0, s0
	ds_write_b16 v41, v0 offset:44416
	v_mul_f32_e32 v0, v29, v36
	v_cvt_pk_bf16_f32 v0, v0, s0
	ds_write_b16 v41, v0 offset:44480
	v_mul_f32_e32 v0, v14, v37
	v_cvt_pk_bf16_f32 v0, v0, s0
	ds_write_b16 v41, v0 offset:45056
	v_mul_f32_e32 v0, v30, v37
	v_cvt_pk_bf16_f32 v0, v0, s0
	ds_write_b16 v41, v0 offset:45120
	v_mul_f32_e32 v0, v15, v38
	v_cvt_pk_bf16_f32 v0, v0, s0
	ds_write_b16 v41, v0 offset:45184
	v_mul_f32_e32 v0, v31, v38
	v_cvt_pk_bf16_f32 v0, v0, s0
	ds_write_b16 v41, v0 offset:45248
	v_mul_f32_e32 v0, v16, v39
	v_cvt_pk_bf16_f32 v0, v0, s0
	ds_write_b16 v41, v0 offset:45312
	v_mul_f32_e32 v0, v32, v39
	v_cvt_pk_bf16_f32 v0, v0, s0
	ds_write_b16 v41, v0 offset:45376
	v_mul_f32_e32 v0, v17, v40
	v_cvt_pk_bf16_f32 v0, v0, s0
	ds_write_b16 v41, v0 offset:45440
	v_mul_f32_e32 v0, v33, v40
	v_cvt_pk_bf16_f32 v2, v2, s0
	v_cvt_pk_bf16_f32 v0, v0, s0
	ds_write_b16 v41, v2 offset:44032
	ds_write_b16 v41, v0 offset:45504
	v_add_u32_e32 v0, s6, v138
	v_readlane_b32 s8, v243, 9
	s_waitcnt lgkmcnt(0)
	v_add_u32_e32 v2, v0, v159
	s_lshl_b32 s7, s8, 1
	ds_read_b128 v[2:5], v2 offset:41984
	v_add_u32_e32 v6, v0, v160
	s_add_u32 s0, s0, s7
	ds_read_b128 v[6:9], v6 offset:41984
	s_addc_u32 s1, s1, 0
	v_mov_b32_e32 v139, v1
	v_lshl_add_u64 v[10:11], s[0:1], 0, v[138:139]
	v_mov_b32_e32 v141, v1
	v_lshl_add_u64 v[12:13], v[10:11], 0, v[140:141]
	v_mov_b32_e32 v143, v1
	s_waitcnt lgkmcnt(1)
	global_store_dwordx4 v[12:13], v[2:5], off
	v_mov_b32_e32 v145, v1
	v_lshl_add_u64 v[12:13], v[10:11], 0, v[144:145]
	v_lshl_add_u64 v[2:3], v[10:11], 0, v[142:143]
	s_waitcnt lgkmcnt(0)
	global_store_dwordx4 v[2:3], v[6:9], off
	v_add_u32_e32 v2, v0, v161
	ds_read_b128 v[2:5], v2 offset:41984
	v_add_u32_e32 v0, v0, v162
	ds_read_b128 v[6:9], v0 offset:41984
	v_mov_b32_e32 v147, v1
	s_waitcnt lgkmcnt(1)
	global_store_dwordx4 v[12:13], v[2:5], off
	v_readlane_b32 s9, v243, 10
	s_nop 0
	v_lshl_add_u64 v[2:3], v[10:11], 0, v[146:147]
	s_waitcnt lgkmcnt(0)
	global_store_dwordx4 v[2:3], v[6:9], off
	s_waitcnt lgkmcnt(0)
	s_barrier
	s_branch .LBB0_60
